# baseline (speedup 1.0000x reference)
; __device__ __forceinline__ float bf2f(u16 h) { return __uint_as_float(((unsigned)h) << 16); }
; __device__ __forceinline__ float sigmoidf_(float x) { return 1.f / (1.f + __expf(-x)); }
; __global__ void __launch_bounds__(512) mega(Params Pk) {
;     ...
; #pragma unroll
;         for (int nb = 0; nb < 4; ++nb)
; #pragma unroll
;           for (int j = 0; j < 4; ++j) {
;             const int rs = wid * 16 + (lane >> 4) * 4 + j; const int col = tk * 64 + nb * 16 + (lane & 15);
;             const float g = sigmoidf_(bf2f(PROJ[(long)(NP + rs) * NC + OG + br * 2048 + col]));
;             atomicAdd(MRGF + (long)rs * D + col, g * acc[nb][j]);
;           }
.LBB0_1095:
	s_lshl_b32 s6, s10, 11
	s_ashr_i32 s7, s6, 31
	s_waitcnt vmcnt(1)
	v_lshl_or_b32 v28, s1, 6, v74
	s_lshl_b64 s[6:7], s[6:7], 1
	v_lshl_add_u64 v[26:27], v[38:39], 0, s[6:7]
	v_lshlrev_b32_e32 v30, 1, v28
	v_mov_b32_e32 v31, v3
	v_lshlrev_b32_e32 v24, 2, v28
	v_mov_b32_e32 v25, v3
	v_lshl_add_u64 v[28:29], v[26:27], 0, v[30:31]
	v_lshl_add_u64 v[216:217], v[42:43], 0, s[6:7]
	v_lshl_add_u64 v[216:217], v[216:217], 0, v[30:31]
	v_lshl_add_u64 v[218:219], v[46:47], 0, s[6:7]
	v_lshl_add_u64 v[218:219], v[218:219], 0, v[30:31]
	v_lshl_add_u64 v[220:221], v[50:51], 0, s[6:7]
	v_lshl_add_u64 v[220:221], v[220:221], 0, v[30:31]
	global_load_ushort v200, v[28:29], off
	global_load_ushort v201, v[216:217], off
	global_load_ushort v202, v[218:219], off
	global_load_ushort v203, v[220:221], off
	global_load_ushort v204, v[28:29], off offset:32
	global_load_ushort v205, v[216:217], off offset:32
	global_load_ushort v206, v[218:219], off offset:32
	global_load_ushort v207, v[220:221], off offset:32
	global_load_ushort v208, v[28:29], off offset:64
	global_load_ushort v209, v[216:217], off offset:64
	global_load_ushort v210, v[218:219], off offset:64
	global_load_ushort v211, v[220:221], off offset:64
	global_load_ushort v212, v[28:29], off offset:96
	global_load_ushort v213, v[216:217], off offset:96
	global_load_ushort v214, v[218:219], off offset:96
	global_load_ushort v215, v[220:221], off offset:96
	s_waitcnt vmcnt(0)
	v_lshl_add_u64 v[32:33], s[4:5], 0, v[24:25]
	v_mov_b32_e32 v25, v200
	s_mov_b32 s1, s48
	s_waitcnt vmcnt(0)
	v_lshlrev_b32_e32 v25, 16, v25
	v_mul_f32_e32 v25, 0xbfb8aa3b, v25
	v_exp_f32_e32 v25, v25
	s_nop 0
	v_add_f32_e32 v25, 1.0, v25
	v_div_scale_f32 v26, s[8:9], v25, v25, 1.0
	v_rcp_f32_e32 v27, v26
	s_nop 0
	v_fma_f32 v34, -v26, v27, 1.0
	v_fmac_f32_e32 v27, v34, v27
	v_div_scale_f32 v34, vcc, 1.0, v25, 1.0
	v_mul_f32_e32 v35, v34, v27
	v_fma_f32 v66, -v26, v35, v34
	v_fmac_f32_e32 v35, v66, v27
	v_fma_f32 v26, -v26, v35, v34
	v_div_fmas_f32 v26, v26, v27, v35
	v_div_fixup_f32 v25, v26, v25, 1.0
	v_lshl_add_u64 v[26:27], v[32:33], 0, v[40:41]
	v_mul_f32_e32 v20, v20, v25
	global_atomic_add_f32 v[26:27], v20, off
	v_lshl_add_u64 v[26:27], v[42:43], 0, s[6:7]
	v_lshl_add_u64 v[26:27], v[26:27], 0, v[30:31]
	v_mov_b32_e32 v20, v201
	v_lshlrev_b32_e32 v20, 16, v20
	v_mul_f32_e32 v20, 0xbfb8aa3b, v20
	v_exp_f32_e32 v20, v20
	s_nop 0
	v_add_f32_e32 v20, 1.0, v20
	v_div_scale_f32 v25, s[8:9], v20, v20, 1.0
	v_rcp_f32_e32 v34, v25
	s_nop 0
	v_fma_f32 v35, -v25, v34, 1.0
	v_fmac_f32_e32 v34, v35, v34
	v_div_scale_f32 v35, vcc, 1.0, v20, 1.0
	v_mul_f32_e32 v66, v35, v34
	v_fma_f32 v67, -v25, v66, v35
	v_fmac_f32_e32 v66, v67, v34
	v_fma_f32 v25, -v25, v66, v35
	v_div_fmas_f32 v25, v25, v34, v66
	v_div_fixup_f32 v20, v25, v20, 1.0
	v_lshl_add_u64 v[34:35], v[32:33], 0, v[44:45]
	v_mul_f32_e32 v20, v21, v20
	global_atomic_add_f32 v[34:35], v20, off
	v_lshl_add_u64 v[20:21], v[46:47], 0, s[6:7]
	v_lshl_add_u64 v[20:21], v[20:21], 0, v[30:31]
	v_mov_b32_e32 v25, v202
	v_lshlrev_b32_e32 v25, 16, v25
	v_mul_f32_e32 v25, 0xbfb8aa3b, v25
	v_exp_f32_e32 v25, v25
	s_nop 0
	v_add_f32_e32 v25, 1.0, v25
	v_div_scale_f32 v34, s[8:9], v25, v25, 1.0
	v_rcp_f32_e32 v35, v34
	s_nop 0
	v_fma_f32 v66, -v34, v35, 1.0
	v_fmac_f32_e32 v35, v66, v35
	v_div_scale_f32 v66, vcc, 1.0, v25, 1.0
	v_mul_f32_e32 v67, v66, v35
	v_fma_f32 v68, -v34, v67, v66
	v_fmac_f32_e32 v67, v68, v35
	v_fma_f32 v34, -v34, v67, v66
	v_div_fmas_f32 v34, v34, v35, v67
	v_div_fixup_f32 v25, v34, v25, 1.0
	v_lshl_add_u64 v[34:35], v[32:33], 0, v[48:49]
	v_mul_f32_e32 v22, v22, v25
	global_atomic_add_f32 v[34:35], v22, off
	v_lshl_add_u64 v[34:35], v[50:51], 0, s[6:7]
	v_lshl_add_u64 v[30:31], v[34:35], 0, v[30:31]
	v_mov_b32_e32 v22, v203
	v_lshl_add_u64 v[32:33], v[32:33], 0, v[52:53]
	v_lshlrev_b32_e32 v22, 16, v22
	v_mul_f32_e32 v22, 0xbfb8aa3b, v22
	v_exp_f32_e32 v22, v22
	s_nop 0
	v_add_f32_e32 v22, 1.0, v22
	v_div_scale_f32 v25, s[6:7], v22, v22, 1.0
	v_rcp_f32_e32 v34, v25
	s_nop 0
	v_fma_f32 v35, -v25, v34, 1.0
	v_fmac_f32_e32 v34, v35, v34
	v_div_scale_f32 v35, vcc, 1.0, v22, 1.0
	v_mul_f32_e32 v66, v35, v34
	v_fma_f32 v67, -v25, v66, v35
	v_fmac_f32_e32 v66, v67, v34
	v_fma_f32 v25, -v25, v66, v35
	v_div_fmas_f32 v25, v25, v34, v66
	v_div_fixup_f32 v22, v25, v22, 1.0
	v_mul_f32_e32 v22, v23, v22
	global_atomic_add_f32 v[32:33], v22, off
	v_mov_b32_e32 v22, v204
	v_lshlrev_b32_e32 v22, 16, v22
	v_mul_f32_e32 v22, 0xbfb8aa3b, v22
	v_exp_f32_e32 v22, v22
	s_nop 0
	v_add_f32_e32 v22, 1.0, v22
	v_div_scale_f32 v23, s[6:7], v22, v22, 1.0
	v_rcp_f32_e32 v25, v23
	s_nop 0
	v_fma_f32 v32, -v23, v25, 1.0
	v_fmac_f32_e32 v25, v32, v25
	v_div_scale_f32 v32, vcc, 1.0, v22, 1.0
	v_mul_f32_e32 v33, v32, v25
	v_fma_f32 v34, -v23, v33, v32
	v_fmac_f32_e32 v33, v34, v25
	v_fma_f32 v23, -v23, v33, v32
	v_div_fmas_f32 v23, v23, v25, v33
	v_div_fixup_f32 v25, v23, v22, 1.0
	v_or_b32_e32 v22, 64, v24
	v_mov_b32_e32 v23, v3
	v_lshl_add_u64 v[32:33], v[54:55], 0, v[22:23]
	v_mul_f32_e32 v16, v16, v25
	global_atomic_add_f32 v[32:33], v16, off
	v_mov_b32_e32 v16, v205
	v_lshlrev_b32_e32 v16, 16, v16
	v_mul_f32_e32 v16, 0xbfb8aa3b, v16
	v_exp_f32_e32 v16, v16
	s_nop 0
	v_add_f32_e32 v16, 1.0, v16
	v_div_scale_f32 v25, s[6:7], v16, v16, 1.0
	v_rcp_f32_e32 v32, v25
	s_nop 0
	v_fma_f32 v33, -v25, v32, 1.0
	v_fmac_f32_e32 v32, v33, v32
	v_div_scale_f32 v33, vcc, 1.0, v16, 1.0
	v_mul_f32_e32 v34, v33, v32
	v_fma_f32 v35, -v25, v34, v33
	v_fmac_f32_e32 v34, v35, v32
	v_fma_f32 v25, -v25, v34, v33
	v_div_fmas_f32 v25, v25, v32, v34
	v_div_fixup_f32 v16, v25, v16, 1.0
	v_lshl_add_u64 v[32:33], v[56:57], 0, v[22:23]
; __device__ __forceinline__ float bf2f(u16 h) { return __uint_as_float(((unsigned)h) << 16); }
; __device__ __forceinline__ float sigmoidf_(float x) { return 1.f / (1.f + __expf(-x)); }
; __global__ void __launch_bounds__(512) mega(Params Pk) {
;     ...
; #pragma unroll
;         for (int nb = 0; nb < 4; ++nb)
; #pragma unroll
;           for (int j = 0; j < 4; ++j) {
;             const int rs = wid * 16 + (lane >> 4) * 4 + j; const int col = tk * 64 + nb * 16 + (lane & 15);
;             const float g = sigmoidf_(bf2f(PROJ[(long)(NP + rs) * NC + OG + br * 2048 + col]));
;             atomicAdd(MRGF + (long)rs * D + col, g * acc[nb][j]);
;           }
	v_mul_f32_e32 v16, v17, v16
	global_atomic_add_f32 v[32:33], v16, off
	v_mov_b32_e32 v16, v206
	v_lshlrev_b32_e32 v16, 16, v16
	v_mul_f32_e32 v16, 0xbfb8aa3b, v16
	v_exp_f32_e32 v16, v16
	s_nop 0
	v_add_f32_e32 v16, 1.0, v16
	v_div_scale_f32 v17, s[6:7], v16, v16, 1.0
	v_rcp_f32_e32 v25, v17
	s_nop 0
	v_fma_f32 v32, -v17, v25, 1.0
	v_fmac_f32_e32 v25, v32, v25
	v_div_scale_f32 v32, vcc, 1.0, v16, 1.0
	v_mul_f32_e32 v33, v32, v25
	v_fma_f32 v34, -v17, v33, v32
	v_fmac_f32_e32 v33, v34, v25
	v_fma_f32 v17, -v17, v33, v32
	v_div_fmas_f32 v17, v17, v25, v33
	v_div_fixup_f32 v25, v17, v16, 1.0
	v_lshl_add_u64 v[16:17], v[58:59], 0, v[22:23]
	v_mul_f32_e32 v18, v18, v25
	global_atomic_add_f32 v[16:17], v18, off
	v_mov_b32_e32 v16, v207
	v_lshlrev_b32_e32 v16, 16, v16
	v_mul_f32_e32 v16, 0xbfb8aa3b, v16
	v_exp_f32_e32 v16, v16
	s_nop 0
	v_add_f32_e32 v16, 1.0, v16
	v_div_scale_f32 v17, s[6:7], v16, v16, 1.0
	v_rcp_f32_e32 v18, v17
	s_nop 0
	v_fma_f32 v25, -v17, v18, 1.0
	v_fmac_f32_e32 v18, v25, v18
	v_div_scale_f32 v25, vcc, 1.0, v16, 1.0
	v_mul_f32_e32 v32, v25, v18
	v_fma_f32 v33, -v17, v32, v25
	v_fmac_f32_e32 v32, v33, v18
	v_fma_f32 v17, -v17, v32, v25
	v_div_fmas_f32 v17, v17, v18, v32
	v_div_fixup_f32 v18, v17, v16, 1.0
	v_lshl_add_u64 v[16:17], v[60:61], 0, v[22:23]
	v_mul_f32_e32 v18, v19, v18
	global_atomic_add_f32 v[16:17], v18, off
	v_mov_b32_e32 v16, v208
	v_lshlrev_b32_e32 v16, 16, v16
	v_mul_f32_e32 v16, 0xbfb8aa3b, v16
	v_exp_f32_e32 v16, v16
	s_nop 0
	v_add_f32_e32 v16, 1.0, v16
	v_div_scale_f32 v17, s[6:7], v16, v16, 1.0
	v_rcp_f32_e32 v18, v17
	s_nop 0
	v_fma_f32 v19, -v17, v18, 1.0
	v_fmac_f32_e32 v18, v19, v18
	v_div_scale_f32 v19, vcc, 1.0, v16, 1.0
	v_mul_f32_e32 v22, v19, v18
	v_fma_f32 v23, -v17, v22, v19
	v_fmac_f32_e32 v22, v23, v18
	v_fma_f32 v17, -v17, v22, v19
	v_div_fmas_f32 v17, v17, v18, v22
	v_div_fixup_f32 v22, v17, v16, 1.0
	v_or_b32_e32 v16, 0x80, v24
	v_mov_b32_e32 v17, v3
	v_lshl_add_u64 v[18:19], v[54:55], 0, v[16:17]
	v_mul_f32_e32 v12, v12, v22
	global_atomic_add_f32 v[18:19], v12, off
	v_mov_b32_e32 v12, v209
	v_lshlrev_b32_e32 v12, 16, v12
	v_mul_f32_e32 v12, 0xbfb8aa3b, v12
	v_exp_f32_e32 v12, v12
	s_nop 0
	v_add_f32_e32 v12, 1.0, v12
	v_div_scale_f32 v18, s[6:7], v12, v12, 1.0
	v_rcp_f32_e32 v19, v18
	s_nop 0
	v_fma_f32 v22, -v18, v19, 1.0
	v_fmac_f32_e32 v19, v22, v19
	v_div_scale_f32 v22, vcc, 1.0, v12, 1.0
	v_mul_f32_e32 v23, v22, v19
	v_fma_f32 v25, -v18, v23, v22
	v_fmac_f32_e32 v23, v25, v19
	v_fma_f32 v18, -v18, v23, v22
	v_div_fmas_f32 v18, v18, v19, v23
	v_div_fixup_f32 v12, v18, v12, 1.0
	v_lshl_add_u64 v[18:19], v[56:57], 0, v[16:17]
	v_mul_f32_e32 v12, v13, v12
	global_atomic_add_f32 v[18:19], v12, off
	v_mov_b32_e32 v12, v210
	v_lshlrev_b32_e32 v12, 16, v12
	v_mul_f32_e32 v12, 0xbfb8aa3b, v12
	v_exp_f32_e32 v12, v12
	s_nop 0
	v_add_f32_e32 v12, 1.0, v12
	v_div_scale_f32 v13, s[6:7], v12, v12, 1.0
	v_rcp_f32_e32 v18, v13
	s_nop 0
	v_fma_f32 v19, -v13, v18, 1.0
	v_fmac_f32_e32 v18, v19, v18
	v_div_scale_f32 v19, vcc, 1.0, v12, 1.0
	v_mul_f32_e32 v22, v19, v18
	v_fma_f32 v23, -v13, v22, v19
	v_fmac_f32_e32 v22, v23, v18
	v_fma_f32 v13, -v13, v22, v19
	v_div_fmas_f32 v13, v13, v18, v22
	v_div_fixup_f32 v18, v13, v12, 1.0
	v_lshl_add_u64 v[12:13], v[58:59], 0, v[16:17]
	v_mul_f32_e32 v14, v14, v18
	global_atomic_add_f32 v[12:13], v14, off
	v_mov_b32_e32 v12, v211
	v_lshlrev_b32_e32 v12, 16, v12
	v_mul_f32_e32 v12, 0xbfb8aa3b, v12
	v_exp_f32_e32 v12, v12
	s_nop 0
	v_add_f32_e32 v12, 1.0, v12
	v_div_scale_f32 v13, s[6:7], v12, v12, 1.0
	v_rcp_f32_e32 v14, v13
	s_nop 0
	v_fma_f32 v18, -v13, v14, 1.0
	v_fmac_f32_e32 v14, v18, v14
	v_div_scale_f32 v18, vcc, 1.0, v12, 1.0
	v_mul_f32_e32 v19, v18, v14
	v_fma_f32 v22, -v13, v19, v18
	v_fmac_f32_e32 v19, v22, v14
	v_fma_f32 v13, -v13, v19, v18
	v_div_fmas_f32 v13, v13, v14, v19
	v_div_fixup_f32 v14, v13, v12, 1.0
	v_lshl_add_u64 v[12:13], v[60:61], 0, v[16:17]
	v_mul_f32_e32 v14, v15, v14
	global_atomic_add_f32 v[12:13], v14, off
	v_mov_b32_e32 v12, v212
	v_lshlrev_b32_e32 v12, 16, v12
	v_mul_f32_e32 v12, 0xbfb8aa3b, v12
	v_exp_f32_e32 v12, v12
	s_nop 0
	v_add_f32_e32 v12, 1.0, v12
	v_div_scale_f32 v13, s[6:7], v12, v12, 1.0
	v_rcp_f32_e32 v14, v13
	s_nop 0
	v_fma_f32 v15, -v13, v14, 1.0
	v_fmac_f32_e32 v14, v15, v14
	v_div_scale_f32 v15, vcc, 1.0, v12, 1.0
	v_mul_f32_e32 v16, v15, v14
	v_fma_f32 v17, -v13, v16, v15
	v_fmac_f32_e32 v16, v17, v14
	v_fma_f32 v13, -v13, v16, v15
	v_div_fmas_f32 v13, v13, v14, v16
	v_div_fixup_f32 v16, v13, v12, 1.0
	v_or_b32_e32 v12, 0xc0, v24
	v_mov_b32_e32 v13, v3
	v_lshl_add_u64 v[14:15], v[54:55], 0, v[12:13]
	v_mul_f32_e32 v8, v8, v16
	global_atomic_add_f32 v[14:15], v8, off
	v_mov_b32_e32 v8, v213
	v_lshlrev_b32_e32 v8, 16, v8
	v_mul_f32_e32 v8, 0xbfb8aa3b, v8
	v_exp_f32_e32 v8, v8
	s_nop 0
	v_add_f32_e32 v8, 1.0, v8
	v_div_scale_f32 v14, s[6:7], v8, v8, 1.0
	v_rcp_f32_e32 v15, v14
	s_nop 0
	v_fma_f32 v16, -v14, v15, 1.0
	v_fmac_f32_e32 v15, v16, v15
	v_div_scale_f32 v16, vcc, 1.0, v8, 1.0
	v_mul_f32_e32 v17, v16, v15
	v_fma_f32 v18, -v14, v17, v16
	v_fmac_f32_e32 v17, v18, v15
	v_fma_f32 v14, -v14, v17, v16
	v_div_fmas_f32 v14, v14, v15, v17
	v_div_fixup_f32 v8, v14, v8, 1.0
	v_lshl_add_u64 v[14:15], v[56:57], 0, v[12:13]
	v_mul_f32_e32 v8, v9, v8
	global_atomic_add_f32 v[14:15], v8, off
	v_mov_b32_e32 v8, v214
	v_lshlrev_b32_e32 v8, 16, v8
	v_mul_f32_e32 v8, 0xbfb8aa3b, v8
	v_exp_f32_e32 v8, v8
	s_nop 0
	v_add_f32_e32 v8, 1.0, v8
	v_div_scale_f32 v9, s[6:7], v8, v8, 1.0
	v_rcp_f32_e32 v14, v9
	s_nop 0
	v_fma_f32 v15, -v9, v14, 1.0
	v_fmac_f32_e32 v14, v15, v14
	v_div_scale_f32 v15, vcc, 1.0, v8, 1.0
	v_mul_f32_e32 v16, v15, v14
	v_fma_f32 v17, -v9, v16, v15
	v_fmac_f32_e32 v16, v17, v14
	v_fma_f32 v9, -v9, v16, v15
	v_div_fmas_f32 v9, v9, v14, v16
	v_div_fixup_f32 v14, v9, v8, 1.0
	v_lshl_add_u64 v[8:9], v[58:59], 0, v[12:13]
	v_mul_f32_e32 v10, v10, v14
	global_atomic_add_f32 v[8:9], v10, off
	v_mov_b32_e32 v8, v215
	v_lshlrev_b32_e32 v8, 16, v8
	v_mul_f32_e32 v8, 0xbfb8aa3b, v8
	v_exp_f32_e32 v8, v8
	s_nop 0
	v_add_f32_e32 v8, 1.0, v8
	v_div_scale_f32 v9, s[6:7], v8, v8, 1.0
	v_rcp_f32_e32 v10, v9
	s_nop 0
	v_fma_f32 v14, -v9, v10, 1.0
	v_fmac_f32_e32 v10, v14, v10
	v_div_scale_f32 v14, vcc, 1.0, v8, 1.0
	v_mul_f32_e32 v15, v14, v10
	v_fma_f32 v16, -v9, v15, v14
	v_fmac_f32_e32 v15, v16, v10
	v_fma_f32 v9, -v9, v15, v14
	v_div_fmas_f32 v9, v9, v10, v15
	v_div_fixup_f32 v10, v9, v8, 1.0
	v_lshl_add_u64 v[8:9], v[60:61], 0, v[12:13]
	v_mul_f32_e32 v10, v11, v10
	global_atomic_add_f32 v[8:9], v10, off
	s_add_i32 s0, s1, s0
	s_cmpk_gt_i32 s0, 0xbf
	s_cbranch_scc1 .LBB0_1102

; #define SK_LOAD(KK) do { rb = *(const uint4*)(bp + (KK)); \
;     if constexpr (AF32) { fa[0] = *(const float4*)(fp0 + (KK)); fa[1] = *(const float4*)(fp0 + (KK) + 4); \
;                           fa[2] = *(const float4*)(fp1 + (KK)); fa[3] = *(const float4*)(fp1 + (KK) + 4); } \
;     else { ra0 = *(const uint4*)(ap0 + (KK)); ra1 = *(const uint4*)(ap1 + (KK)); } } while (0)
; template <bool AF32>
; __device__ __forceinline__ void skinny_gemm(const void* __restrict__ Av, long lda, const u16* __restrict__ Bt, long ldb, int kb, int ke,
;                                             f32x4* acc, char* smem, int tid) {
;     ...
;   SK_LOAD(kb);
;   for (int k0 = kb; k0 < ke; k0 += 64) {
;     if constexpr (AF32) {
;       float f0[8] = {fa[0].x, fa[0].y, fa[0].z, fa[0].w, fa[1].x, fa[1].y, fa[1].z, fa[1].w};
;       float f1[8] = {fa[2].x, fa[2].y, fa[2].z, fa[2].w, fa[3].x, fa[3].y, fa[3].z, fa[3].w};
;       ra0 = pack8(f0); ra1 = pack8(f1);
;     }
;     *(uint4*)(As + r0 * 72 + v0 * 8) = ra0;
;     *(uint4*)(As + (r0 + 64) * 72 + v0 * 8) = ra1;
;     *(uint4*)(Bs + r0 * 72 + v0 * 8) = rb;
;     __syncthreads();
;     if (k0 + 64 < ke) SK_LOAD(k0 + 64);
; #pragma unroll
;     for (int ks = 0; ks < 2; ++ks) {
;       const bf16x8 af = *(const bf16x8*)(As + (wid * 16 + fr) * 72 + ks * 32 + fq * 8);
; #pragma unroll
;       for (int nb = 0; nb < 4; ++nb) {
;         const bf16x8 bf = *(const bf16x8*)(Bs + (nb * 16 + fr) * 72 + ks * 32 + fq * 8);
;         acc[nb] = __builtin_amdgcn_mfma_f32_16x16x32_bf16(af, bf, acc[nb], 0, 0, 0);
;       }
;     }
;     __syncthreads();
;   }
; __global__ void __launch_bounds__(512) mega(Params Pk) {
;     ...
;         const int tk = task & 31, ksp = task >> 5;
;         f32x4 acc[4] = {};
;         skinny_gemm<false>(ACT + (long)NP * DFF, DFF, W2T + (long)tk * 64 * DFF, DFF, ksp * 1024, ksp * 1024 + 1024, acc, smem, tid_);
.LBB0_1317:
	s_lshl_b32 s6, s0, 5
	s_and_b32 s1, s0, 31
	s_and_b32 s6, s6, 0xfffffc00
	s_lshl_b32 s26, s1, 20
	s_ashr_i32 s7, s6, 31
	v_lshl_add_u64 v[8:9], v[0:1], 0, s[26:27]
	s_lshl_b64 s[8:9], s[6:7], 1
	v_lshl_add_u64 v[10:11], v[38:39], 0, s[8:9]
	v_lshl_add_u64 v[12:13], v[36:37], 0, s[8:9]
	v_lshl_add_u64 v[8:9], v[8:9], 0, s[8:9]
	v_mov_b64_e32 v[194:195], v[10:11]
	v_mov_b64_e32 v[192:193], v[12:13]
	v_mov_b64_e32 v[196:197], v[8:9]
	global_load_dwordx4 v[16:19], v[10:11], off
	s_nop 0
	global_load_dwordx4 v[12:15], v[12:13], off
	s_or_b32 s7, s6, 0x3c0
	global_load_dwordx4 v[8:11], v[8:9], off
	s_waitcnt vmcnt(11)
	v_lshl_add_u64 v[52:53], v[50:51], 0, s[8:9]
	v_readlane_b32 s8, v251, 19
	v_readlane_b32 s9, v251, 20
	s_add_u32 s8, s8, s26
	v_mov_b32_e32 v20, 0
	s_addc_u32 s9, 0, 0
	v_mov_b32_e32 v21, v20
	v_mov_b32_e32 v22, v20
	v_mov_b32_e32 v23, v20
	v_mov_b32_e32 v24, v20
	v_mov_b32_e32 v25, v20
	v_mov_b32_e32 v26, v20
	v_mov_b32_e32 v27, v20
	v_mov_b32_e32 v28, v20
	v_mov_b32_e32 v29, v20
	v_mov_b32_e32 v30, v20
	v_mov_b32_e32 v31, v20
	v_mov_b32_e32 v32, v20
	v_mov_b32_e32 v33, v20
	v_mov_b32_e32 v34, v20
	v_mov_b32_e32 v35, v20
	v_mov_b32_e32 v198, 0x80
	v_mov_b32_e32 v199, 0
	s_mov_b32 s10, 0
	v_lshl_add_u64 v[194:195], v[194:195], 0, v[198:199]
	v_lshl_add_u64 v[192:193], v[192:193], 0, v[198:199]
	v_lshl_add_u64 v[196:197], v[196:197], 0, v[198:199]
	global_load_dwordx4 v[64:67], v[194:195], off
	global_load_dwordx4 v[60:63], v[192:193], off
	global_load_dwordx4 v[68:71], v[196:197], off
	v_lshl_add_u64 v[194:195], v[194:195], 0, v[198:199]
	v_lshl_add_u64 v[192:193], v[192:193], 0, v[198:199]
	v_lshl_add_u64 v[196:197], v[196:197], 0, v[198:199]
	global_load_dwordx4 v[76:79], v[194:195], off
	global_load_dwordx4 v[72:75], v[192:193], off
	global_load_dwordx4 v[80:83], v[196:197], off
.Lsk11_loop:
	v_lshl_add_u64 v[194:195], v[194:195], 0, v[198:199]
	v_lshl_add_u64 v[192:193], v[192:193], 0, v[198:199]
	v_lshl_add_u64 v[196:197], v[196:197], 0, v[198:199]
	global_load_dwordx4 v[88:91], v[194:195], off
	global_load_dwordx4 v[84:87], v[192:193], off
	global_load_dwordx4 v[92:95], v[196:197], off
	s_waitcnt vmcnt(9)
	ds_write_b128 v57, v[12:15]
	ds_write_b128 v41, v[16:19]
	ds_write_b128 v57, v[8:11] offset:18432
	s_waitcnt lgkmcnt(0)
	s_barrier
	ds_read_b128 v[208:211], v40
	ds_read_b128 v[216:219], v58 offset:18432
	ds_read_b128 v[220:223], v58 offset:20736
	ds_read_b128 v[234:237], v58 offset:23040
	ds_read_b128 v[238:241], v58 offset:25344
	ds_read_b128 v[212:215], v40 offset:64
	ds_read_b128 v[242:245], v58 offset:18496
	ds_read_b128 v[246:249], v58 offset:20800
	ds_read_b128 v[200:203], v58 offset:23104
	ds_read_b128 v[204:207], v58 offset:25408
	s_waitcnt lgkmcnt(8)
	v_mfma_f32_16x16x32_bf16 v[20:23], v[208:211], v[216:219], v[20:23]
	s_waitcnt lgkmcnt(7)
	v_mfma_f32_16x16x32_bf16 v[24:27], v[208:211], v[220:223], v[24:27]
	s_waitcnt lgkmcnt(6)
	v_mfma_f32_16x16x32_bf16 v[28:31], v[208:211], v[234:237], v[28:31]
	s_waitcnt lgkmcnt(5)
	v_mfma_f32_16x16x32_bf16 v[32:35], v[208:211], v[238:241], v[32:35]
	s_waitcnt lgkmcnt(3)
	v_mfma_f32_16x16x32_bf16 v[20:23], v[212:215], v[242:245], v[20:23]
	s_waitcnt lgkmcnt(2)
	v_mfma_f32_16x16x32_bf16 v[24:27], v[212:215], v[246:249], v[24:27]
	s_waitcnt lgkmcnt(1)
	v_mfma_f32_16x16x32_bf16 v[28:31], v[212:215], v[200:203], v[28:31]
	s_waitcnt lgkmcnt(0)
	s_barrier
	v_mfma_f32_16x16x32_bf16 v[32:35], v[212:215], v[204:207], v[32:35]
	v_lshl_add_u64 v[194:195], v[194:195], 0, v[198:199]
	v_lshl_add_u64 v[192:193], v[192:193], 0, v[198:199]
	v_lshl_add_u64 v[196:197], v[196:197], 0, v[198:199]
	global_load_dwordx4 v[16:19], v[194:195], off
	global_load_dwordx4 v[12:15], v[192:193], off
	global_load_dwordx4 v[8:11], v[196:197], off
	s_waitcnt vmcnt(9)
	ds_write_b128 v57, v[60:63]
	ds_write_b128 v41, v[64:67]
	ds_write_b128 v57, v[68:71] offset:18432
	s_waitcnt lgkmcnt(0)
	s_barrier
	ds_read_b128 v[208:211], v40
	ds_read_b128 v[216:219], v58 offset:18432
	ds_read_b128 v[220:223], v58 offset:20736
	ds_read_b128 v[234:237], v58 offset:23040
	ds_read_b128 v[238:241], v58 offset:25344
	ds_read_b128 v[212:215], v40 offset:64
	ds_read_b128 v[242:245], v58 offset:18496
	ds_read_b128 v[246:249], v58 offset:20800
	ds_read_b128 v[200:203], v58 offset:23104
	ds_read_b128 v[204:207], v58 offset:25408
	s_waitcnt lgkmcnt(8)
	v_mfma_f32_16x16x32_bf16 v[20:23], v[208:211], v[216:219], v[20:23]
	s_waitcnt lgkmcnt(7)
	v_mfma_f32_16x16x32_bf16 v[24:27], v[208:211], v[220:223], v[24:27]
	s_waitcnt lgkmcnt(6)
	v_mfma_f32_16x16x32_bf16 v[28:31], v[208:211], v[234:237], v[28:31]
	s_waitcnt lgkmcnt(5)
	v_mfma_f32_16x16x32_bf16 v[32:35], v[208:211], v[238:241], v[32:35]
	s_waitcnt lgkmcnt(3)
	v_mfma_f32_16x16x32_bf16 v[20:23], v[212:215], v[242:245], v[20:23]
	s_waitcnt lgkmcnt(2)
	v_mfma_f32_16x16x32_bf16 v[24:27], v[212:215], v[246:249], v[24:27]
	s_waitcnt lgkmcnt(1)
	v_mfma_f32_16x16x32_bf16 v[28:31], v[212:215], v[200:203], v[28:31]
	s_waitcnt lgkmcnt(0)
	s_barrier
	v_mfma_f32_16x16x32_bf16 v[32:35], v[212:215], v[204:207], v[32:35]
	v_lshl_add_u64 v[194:195], v[194:195], 0, v[198:199]
	v_lshl_add_u64 v[192:193], v[192:193], 0, v[198:199]
	v_lshl_add_u64 v[196:197], v[196:197], 0, v[198:199]
	global_load_dwordx4 v[64:67], v[194:195], off
	global_load_dwordx4 v[60:63], v[192:193], off
	global_load_dwordx4 v[68:71], v[196:197], off
	s_waitcnt vmcnt(9)
	ds_write_b128 v57, v[72:75]
	ds_write_b128 v41, v[76:79]
	ds_write_b128 v57, v[80:83] offset:18432
	s_waitcnt lgkmcnt(0)
	s_barrier
; #define SK_LOAD(KK) do { rb = *(const uint4*)(bp + (KK)); \
;     if constexpr (AF32) { fa[0] = *(const float4*)(fp0 + (KK)); fa[1] = *(const float4*)(fp0 + (KK) + 4); \
;                           fa[2] = *(const float4*)(fp1 + (KK)); fa[3] = *(const float4*)(fp1 + (KK) + 4); } \
;     else { ra0 = *(const uint4*)(ap0 + (KK)); ra1 = *(const uint4*)(ap1 + (KK)); } } while (0)
; template <bool AF32>
; __device__ __forceinline__ void skinny_gemm(const void* __restrict__ Av, long lda, const u16* __restrict__ Bt, long ldb, int kb, int ke,
;                                             f32x4* acc, char* smem, int tid) {
;     ...
;   for (int k0 = kb; k0 < ke; k0 += 64) {
;     if constexpr (AF32) {
;       float f0[8] = {fa[0].x, fa[0].y, fa[0].z, fa[0].w, fa[1].x, fa[1].y, fa[1].z, fa[1].w};
;       float f1[8] = {fa[2].x, fa[2].y, fa[2].z, fa[2].w, fa[3].x, fa[3].y, fa[3].z, fa[3].w};
;       ra0 = pack8(f0); ra1 = pack8(f1);
;     }
;     *(uint4*)(As + r0 * 72 + v0 * 8) = ra0;
;     *(uint4*)(As + (r0 + 64) * 72 + v0 * 8) = ra1;
;     *(uint4*)(Bs + r0 * 72 + v0 * 8) = rb;
;     __syncthreads();
;     if (k0 + 64 < ke) SK_LOAD(k0 + 64);
; #pragma unroll
;     for (int ks = 0; ks < 2; ++ks) {
;       const bf16x8 af = *(const bf16x8*)(As + (wid * 16 + fr) * 72 + ks * 32 + fq * 8);
; #pragma unroll
;       for (int nb = 0; nb < 4; ++nb) {
;         const bf16x8 bf = *(const bf16x8*)(Bs + (nb * 16 + fr) * 72 + ks * 32 + fq * 8);
;         acc[nb] = __builtin_amdgcn_mfma_f32_16x16x32_bf16(af, bf, acc[nb], 0, 0, 0);
;       }
;     }
;     __syncthreads();
;   }
	ds_read_b128 v[208:211], v40
	ds_read_b128 v[216:219], v58 offset:18432
	ds_read_b128 v[220:223], v58 offset:20736
	ds_read_b128 v[234:237], v58 offset:23040
	ds_read_b128 v[238:241], v58 offset:25344
	ds_read_b128 v[212:215], v40 offset:64
	ds_read_b128 v[242:245], v58 offset:18496
	ds_read_b128 v[246:249], v58 offset:20800
	ds_read_b128 v[200:203], v58 offset:23104
	ds_read_b128 v[204:207], v58 offset:25408
	s_waitcnt lgkmcnt(8)
	v_mfma_f32_16x16x32_bf16 v[20:23], v[208:211], v[216:219], v[20:23]
	s_waitcnt lgkmcnt(7)
	v_mfma_f32_16x16x32_bf16 v[24:27], v[208:211], v[220:223], v[24:27]
	s_waitcnt lgkmcnt(6)
	v_mfma_f32_16x16x32_bf16 v[28:31], v[208:211], v[234:237], v[28:31]
	s_waitcnt lgkmcnt(5)
	v_mfma_f32_16x16x32_bf16 v[32:35], v[208:211], v[238:241], v[32:35]
	s_waitcnt lgkmcnt(3)
	v_mfma_f32_16x16x32_bf16 v[20:23], v[212:215], v[242:245], v[20:23]
	s_waitcnt lgkmcnt(2)
	v_mfma_f32_16x16x32_bf16 v[24:27], v[212:215], v[246:249], v[24:27]
	s_waitcnt lgkmcnt(1)
	v_mfma_f32_16x16x32_bf16 v[28:31], v[212:215], v[200:203], v[28:31]
	s_waitcnt lgkmcnt(0)
	s_barrier
	v_mfma_f32_16x16x32_bf16 v[32:35], v[212:215], v[204:207], v[32:35]
	v_lshl_add_u64 v[194:195], v[194:195], 0, v[198:199]
	v_lshl_add_u64 v[192:193], v[192:193], 0, v[198:199]
	v_lshl_add_u64 v[196:197], v[196:197], 0, v[198:199]
	global_load_dwordx4 v[76:79], v[194:195], off
	global_load_dwordx4 v[72:75], v[192:193], off
	global_load_dwordx4 v[80:83], v[196:197], off
	s_waitcnt vmcnt(9)
	ds_write_b128 v57, v[84:87]
	ds_write_b128 v41, v[88:91]
	ds_write_b128 v57, v[92:95] offset:18432
	s_waitcnt lgkmcnt(0)
	s_barrier
	ds_read_b128 v[208:211], v40
	ds_read_b128 v[216:219], v58 offset:18432
	ds_read_b128 v[220:223], v58 offset:20736
	ds_read_b128 v[234:237], v58 offset:23040
	ds_read_b128 v[238:241], v58 offset:25344
	ds_read_b128 v[212:215], v40 offset:64
	ds_read_b128 v[242:245], v58 offset:18496
	ds_read_b128 v[246:249], v58 offset:20800
	ds_read_b128 v[200:203], v58 offset:23104
	ds_read_b128 v[204:207], v58 offset:25408
	s_waitcnt lgkmcnt(8)
	v_mfma_f32_16x16x32_bf16 v[20:23], v[208:211], v[216:219], v[20:23]
	s_waitcnt lgkmcnt(7)
	v_mfma_f32_16x16x32_bf16 v[24:27], v[208:211], v[220:223], v[24:27]
	s_waitcnt lgkmcnt(6)
	v_mfma_f32_16x16x32_bf16 v[28:31], v[208:211], v[234:237], v[28:31]
	s_waitcnt lgkmcnt(5)
	v_mfma_f32_16x16x32_bf16 v[32:35], v[208:211], v[238:241], v[32:35]
	s_waitcnt lgkmcnt(3)
	v_mfma_f32_16x16x32_bf16 v[20:23], v[212:215], v[242:245], v[20:23]
	s_waitcnt lgkmcnt(2)
	v_mfma_f32_16x16x32_bf16 v[24:27], v[212:215], v[246:249], v[24:27]
	s_waitcnt lgkmcnt(1)
	v_mfma_f32_16x16x32_bf16 v[28:31], v[212:215], v[200:203], v[28:31]
	s_waitcnt lgkmcnt(0)
	s_barrier
	v_mfma_f32_16x16x32_bf16 v[32:35], v[212:215], v[204:207], v[32:35]
	s_add_i32 s10, s10, 4
	s_cmp_lt_u32 s10, 12
	s_cbranch_scc1 .Lsk11_loop
	v_lshl_add_u64 v[194:195], v[194:195], 0, v[198:199]
	v_lshl_add_u64 v[192:193], v[192:193], 0, v[198:199]
	v_lshl_add_u64 v[196:197], v[196:197], 0, v[198:199]
	global_load_dwordx4 v[88:91], v[194:195], off
	global_load_dwordx4 v[84:87], v[192:193], off
	global_load_dwordx4 v[92:95], v[196:197], off
	s_waitcnt vmcnt(9)
	ds_write_b128 v57, v[12:15]
	ds_write_b128 v41, v[16:19]
	ds_write_b128 v57, v[8:11] offset:18432
	s_waitcnt lgkmcnt(0)
	s_barrier
	ds_read_b128 v[208:211], v40
	ds_read_b128 v[216:219], v58 offset:18432
	ds_read_b128 v[220:223], v58 offset:20736
	ds_read_b128 v[234:237], v58 offset:23040
	ds_read_b128 v[238:241], v58 offset:25344
	ds_read_b128 v[212:215], v40 offset:64
	ds_read_b128 v[242:245], v58 offset:18496
	ds_read_b128 v[246:249], v58 offset:20800
	ds_read_b128 v[200:203], v58 offset:23104
	ds_read_b128 v[204:207], v58 offset:25408
	s_waitcnt lgkmcnt(8)
	v_mfma_f32_16x16x32_bf16 v[20:23], v[208:211], v[216:219], v[20:23]
	s_waitcnt lgkmcnt(7)
	v_mfma_f32_16x16x32_bf16 v[24:27], v[208:211], v[220:223], v[24:27]
	s_waitcnt lgkmcnt(6)
	v_mfma_f32_16x16x32_bf16 v[28:31], v[208:211], v[234:237], v[28:31]
	s_waitcnt lgkmcnt(5)
	v_mfma_f32_16x16x32_bf16 v[32:35], v[208:211], v[238:241], v[32:35]
	s_waitcnt lgkmcnt(3)
	v_mfma_f32_16x16x32_bf16 v[20:23], v[212:215], v[242:245], v[20:23]
	s_waitcnt lgkmcnt(2)
	v_mfma_f32_16x16x32_bf16 v[24:27], v[212:215], v[246:249], v[24:27]
	s_waitcnt lgkmcnt(1)
	v_mfma_f32_16x16x32_bf16 v[28:31], v[212:215], v[200:203], v[28:31]
	s_waitcnt lgkmcnt(0)
	s_barrier
; #define SK_LOAD(KK) do { rb = *(const uint4*)(bp + (KK)); \
;     if constexpr (AF32) { fa[0] = *(const float4*)(fp0 + (KK)); fa[1] = *(const float4*)(fp0 + (KK) + 4); \
;                           fa[2] = *(const float4*)(fp1 + (KK)); fa[3] = *(const float4*)(fp1 + (KK) + 4); } \
;     else { ra0 = *(const uint4*)(ap0 + (KK)); ra1 = *(const uint4*)(ap1 + (KK)); } } while (0)
; template <bool AF32>
; __device__ __forceinline__ void skinny_gemm(const void* __restrict__ Av, long lda, const u16* __restrict__ Bt, long ldb, int kb, int ke,
;                                             f32x4* acc, char* smem, int tid) {
;     ...
;   for (int k0 = kb; k0 < ke; k0 += 64) {
;     if constexpr (AF32) {
;       float f0[8] = {fa[0].x, fa[0].y, fa[0].z, fa[0].w, fa[1].x, fa[1].y, fa[1].z, fa[1].w};
;       float f1[8] = {fa[2].x, fa[2].y, fa[2].z, fa[2].w, fa[3].x, fa[3].y, fa[3].z, fa[3].w};
;       ra0 = pack8(f0); ra1 = pack8(f1);
;     }
;     *(uint4*)(As + r0 * 72 + v0 * 8) = ra0;
;     *(uint4*)(As + (r0 + 64) * 72 + v0 * 8) = ra1;
;     *(uint4*)(Bs + r0 * 72 + v0 * 8) = rb;
;     __syncthreads();
;     if (k0 + 64 < ke) SK_LOAD(k0 + 64);
; #pragma unroll
;     for (int ks = 0; ks < 2; ++ks) {
;       const bf16x8 af = *(const bf16x8*)(As + (wid * 16 + fr) * 72 + ks * 32 + fq * 8);
; #pragma unroll
;       for (int nb = 0; nb < 4; ++nb) {
;         const bf16x8 bf = *(const bf16x8*)(Bs + (nb * 16 + fr) * 72 + ks * 32 + fq * 8);
;         acc[nb] = __builtin_amdgcn_mfma_f32_16x16x32_bf16(af, bf, acc[nb], 0, 0, 0);
;       }
;     }
;     __syncthreads();
;   }
	v_mfma_f32_16x16x32_bf16 v[32:35], v[212:215], v[204:207], v[32:35]
	s_waitcnt vmcnt(6)
	ds_write_b128 v57, v[60:63]
	ds_write_b128 v41, v[64:67]
	ds_write_b128 v57, v[68:71] offset:18432
	s_waitcnt lgkmcnt(0)
	s_barrier
	ds_read_b128 v[208:211], v40
	ds_read_b128 v[216:219], v58 offset:18432
	ds_read_b128 v[220:223], v58 offset:20736
	ds_read_b128 v[234:237], v58 offset:23040
	ds_read_b128 v[238:241], v58 offset:25344
	ds_read_b128 v[212:215], v40 offset:64
	ds_read_b128 v[242:245], v58 offset:18496
	ds_read_b128 v[246:249], v58 offset:20800
	ds_read_b128 v[200:203], v58 offset:23104
	ds_read_b128 v[204:207], v58 offset:25408
	s_waitcnt lgkmcnt(8)
	v_mfma_f32_16x16x32_bf16 v[20:23], v[208:211], v[216:219], v[20:23]
	s_waitcnt lgkmcnt(7)
	v_mfma_f32_16x16x32_bf16 v[24:27], v[208:211], v[220:223], v[24:27]
	s_waitcnt lgkmcnt(6)
	v_mfma_f32_16x16x32_bf16 v[28:31], v[208:211], v[234:237], v[28:31]
	s_waitcnt lgkmcnt(5)
	v_mfma_f32_16x16x32_bf16 v[32:35], v[208:211], v[238:241], v[32:35]
	s_waitcnt lgkmcnt(3)
	v_mfma_f32_16x16x32_bf16 v[20:23], v[212:215], v[242:245], v[20:23]
	s_waitcnt lgkmcnt(2)
	v_mfma_f32_16x16x32_bf16 v[24:27], v[212:215], v[246:249], v[24:27]
	s_waitcnt lgkmcnt(1)
	v_mfma_f32_16x16x32_bf16 v[28:31], v[212:215], v[200:203], v[28:31]
	s_waitcnt lgkmcnt(0)
	s_barrier
	v_mfma_f32_16x16x32_bf16 v[32:35], v[212:215], v[204:207], v[32:35]
	s_waitcnt vmcnt(3)
	ds_write_b128 v57, v[72:75]
	ds_write_b128 v41, v[76:79]
	ds_write_b128 v57, v[80:83] offset:18432
	s_waitcnt lgkmcnt(0)
	s_barrier
	ds_read_b128 v[208:211], v40
	ds_read_b128 v[216:219], v58 offset:18432
	ds_read_b128 v[220:223], v58 offset:20736
	ds_read_b128 v[234:237], v58 offset:23040
	ds_read_b128 v[238:241], v58 offset:25344
	ds_read_b128 v[212:215], v40 offset:64
	ds_read_b128 v[242:245], v58 offset:18496
	ds_read_b128 v[246:249], v58 offset:20800
	ds_read_b128 v[200:203], v58 offset:23104
	ds_read_b128 v[204:207], v58 offset:25408
	s_waitcnt lgkmcnt(8)
	v_mfma_f32_16x16x32_bf16 v[20:23], v[208:211], v[216:219], v[20:23]
	s_waitcnt lgkmcnt(7)
	v_mfma_f32_16x16x32_bf16 v[24:27], v[208:211], v[220:223], v[24:27]
	s_waitcnt lgkmcnt(6)
	v_mfma_f32_16x16x32_bf16 v[28:31], v[208:211], v[234:237], v[28:31]
	s_waitcnt lgkmcnt(5)
	v_mfma_f32_16x16x32_bf16 v[32:35], v[208:211], v[238:241], v[32:35]
	s_waitcnt lgkmcnt(3)
	v_mfma_f32_16x16x32_bf16 v[20:23], v[212:215], v[242:245], v[20:23]
	s_waitcnt lgkmcnt(2)
	v_mfma_f32_16x16x32_bf16 v[24:27], v[212:215], v[246:249], v[24:27]
	s_waitcnt lgkmcnt(1)
	v_mfma_f32_16x16x32_bf16 v[28:31], v[212:215], v[200:203], v[28:31]
	s_waitcnt lgkmcnt(0)
	s_barrier
	v_mfma_f32_16x16x32_bf16 v[32:35], v[212:215], v[204:207], v[32:35]
	s_waitcnt vmcnt(0)
	ds_write_b128 v57, v[84:87]
	ds_write_b128 v41, v[88:91]
	ds_write_b128 v57, v[92:95] offset:18432
	s_waitcnt lgkmcnt(0)
	s_barrier
	ds_read_b128 v[208:211], v40
	ds_read_b128 v[216:219], v58 offset:18432
	ds_read_b128 v[220:223], v58 offset:20736
	ds_read_b128 v[234:237], v58 offset:23040
	ds_read_b128 v[238:241], v58 offset:25344
	ds_read_b128 v[212:215], v40 offset:64
	ds_read_b128 v[242:245], v58 offset:18496
	ds_read_b128 v[246:249], v58 offset:20800
	ds_read_b128 v[200:203], v58 offset:23104
	ds_read_b128 v[204:207], v58 offset:25408
	s_waitcnt lgkmcnt(8)
	v_mfma_f32_16x16x32_bf16 v[20:23], v[208:211], v[216:219], v[20:23]
	s_waitcnt lgkmcnt(7)
	v_mfma_f32_16x16x32_bf16 v[24:27], v[208:211], v[220:223], v[24:27]
	s_waitcnt lgkmcnt(6)
	v_mfma_f32_16x16x32_bf16 v[28:31], v[208:211], v[234:237], v[28:31]
	s_waitcnt lgkmcnt(5)
	v_mfma_f32_16x16x32_bf16 v[32:35], v[208:211], v[238:241], v[32:35]
	s_waitcnt lgkmcnt(3)
	v_mfma_f32_16x16x32_bf16 v[20:23], v[212:215], v[242:245], v[20:23]
	s_waitcnt lgkmcnt(2)
	v_mfma_f32_16x16x32_bf16 v[24:27], v[212:215], v[246:249], v[24:27]
	s_waitcnt lgkmcnt(1)
	v_mfma_f32_16x16x32_bf16 v[28:31], v[212:215], v[200:203], v[28:31]
	s_waitcnt lgkmcnt(0)
	s_barrier
	v_mfma_f32_16x16x32_bf16 v[32:35], v[212:215], v[204:207], v[32:35]
	s_branch .LBB0_1316
